# code warm-up in grid barrier, fire-and-forget: wave 2 touches 32 KB of following code (dword per 64 B chunk into v255, no wait), on top of v129
# baseline (speedup 1.0000x reference)
.LBB0_74:
	s_or_b64 exec, exec, s[2:3]
	v_readfirstlane_b32 s4, v0
	s_lshr_b32 s4, s4, 6
	s_cmp_lg_u32 s4, 2
	s_cbranch_scc1 .Lmy_nopf_0
	s_sleep 30
	s_getpc_b64 s[4:5]
	v_and_b32_e32 v2, 63, v0
	v_lshlrev_b32_e32 v2, 6, v2
	global_load_dword v255, v2, s[4:5]
	s_add_u32 s4, s4, 0x1000
	s_addc_u32 s5, s5, 0
	global_load_dword v255, v2, s[4:5]
	s_add_u32 s4, s4, 0x1000
	s_addc_u32 s5, s5, 0
	global_load_dword v255, v2, s[4:5]
	s_add_u32 s4, s4, 0x1000
	s_addc_u32 s5, s5, 0
	global_load_dword v255, v2, s[4:5]
	s_add_u32 s4, s4, 0x1000
	s_addc_u32 s5, s5, 0
	global_load_dword v255, v2, s[4:5]
	s_add_u32 s4, s4, 0x1000
	s_addc_u32 s5, s5, 0
	global_load_dword v255, v2, s[4:5]
	s_add_u32 s4, s4, 0x1000
	s_addc_u32 s5, s5, 0
	global_load_dword v255, v2, s[4:5]
	s_add_u32 s4, s4, 0x1000
	s_addc_u32 s5, s5, 0
	global_load_dword v255, v2, s[4:5]

.LBB0_114:
	s_or_b64 exec, exec, s[0:1]
	v_readfirstlane_b32 s4, v0
	s_lshr_b32 s4, s4, 6
	s_cmp_lg_u32 s4, 2
	s_cbranch_scc1 .Lmy_nopf_1
	s_sleep 30
	s_getpc_b64 s[4:5]
	v_and_b32_e32 v2, 63, v0
	v_lshlrev_b32_e32 v2, 6, v2
	global_load_dword v255, v2, s[4:5]
	s_add_u32 s4, s4, 0x1000
	s_addc_u32 s5, s5, 0
	global_load_dword v255, v2, s[4:5]
	s_add_u32 s4, s4, 0x1000
	s_addc_u32 s5, s5, 0
	global_load_dword v255, v2, s[4:5]
	s_add_u32 s4, s4, 0x1000
	s_addc_u32 s5, s5, 0
	global_load_dword v255, v2, s[4:5]
	s_add_u32 s4, s4, 0x1000
	s_addc_u32 s5, s5, 0
	global_load_dword v255, v2, s[4:5]
	s_add_u32 s4, s4, 0x1000
	s_addc_u32 s5, s5, 0
	global_load_dword v255, v2, s[4:5]
	s_add_u32 s4, s4, 0x1000
	s_addc_u32 s5, s5, 0
	global_load_dword v255, v2, s[4:5]
	s_add_u32 s4, s4, 0x1000
	s_addc_u32 s5, s5, 0
	global_load_dword v255, v2, s[4:5]

	.amdhsa_kernel _Z6mk_fwd4Args
		.amdhsa_group_segment_fixed_size 0
		.amdhsa_private_segment_fixed_size 0
		.amdhsa_kernarg_size 424
		.amdhsa_user_sgpr_count 2
		.amdhsa_user_sgpr_dispatch_ptr 0
		.amdhsa_user_sgpr_queue_ptr 0
		.amdhsa_user_sgpr_kernarg_segment_ptr 1
		.amdhsa_user_sgpr_dispatch_id 0
		.amdhsa_user_sgpr_kernarg_preload_length 0
		.amdhsa_user_sgpr_kernarg_preload_offset 0
		.amdhsa_user_sgpr_private_segment_size 0
		.amdhsa_uses_dynamic_stack 0
		.amdhsa_enable_private_segment 0
		.amdhsa_system_sgpr_workgroup_id_x 1
		.amdhsa_system_sgpr_workgroup_id_y 0
		.amdhsa_system_sgpr_workgroup_id_z 0
		.amdhsa_system_sgpr_workgroup_info 0
		.amdhsa_system_vgpr_workitem_id 0
		.amdhsa_next_free_vgpr 256
		.amdhsa_next_free_sgpr 102
		.amdhsa_accum_offset 256
		.amdhsa_reserve_vcc 1
		.amdhsa_float_round_mode_32 0
		.amdhsa_float_round_mode_16_64 0
		.amdhsa_float_denorm_mode_32 3
		.amdhsa_float_denorm_mode_16_64 3
		.amdhsa_dx10_clamp 1
		.amdhsa_ieee_mode 1
		.amdhsa_fp16_overflow 0
		.amdhsa_tg_split 0
		.amdhsa_exception_fp_ieee_invalid_op 0
		.amdhsa_exception_fp_denorm_src 0
		.amdhsa_exception_fp_ieee_div_zero 0
		.amdhsa_exception_fp_ieee_overflow 0
		.amdhsa_exception_fp_ieee_underflow 0
		.amdhsa_exception_fp_ieee_inexact 0
		.amdhsa_exception_int_div_zero 0
	.end_amdhsa_kernel

amdhsa.kernels:
  - .agpr_count:     0
    .args:
      - .offset:         0
        .size:           168
        .value_kind:     by_value
      - .offset:         168
        .size:           4
        .value_kind:     hidden_block_count_x
      - .offset:         172
        .size:           4
        .value_kind:     hidden_block_count_y
      - .offset:         176
        .size:           4
        .value_kind:     hidden_block_count_z
      - .offset:         180
        .size:           2
        .value_kind:     hidden_group_size_x
      - .offset:         182
        .size:           2
        .value_kind:     hidden_group_size_y
      - .offset:         184
        .size:           2
        .value_kind:     hidden_group_size_z
      - .offset:         186
        .size:           2
        .value_kind:     hidden_remainder_x
      - .offset:         188
        .size:           2
        .value_kind:     hidden_remainder_y
      - .offset:         190
        .size:           2
        .value_kind:     hidden_remainder_z
      - .offset:         208
        .size:           8
        .value_kind:     hidden_global_offset_x
      - .offset:         216
        .size:           8
        .value_kind:     hidden_global_offset_y
      - .offset:         224
        .size:           8
        .value_kind:     hidden_global_offset_z
      - .offset:         232
        .size:           2
        .value_kind:     hidden_grid_dims
      - .offset:         288
        .size:           4
        .value_kind:     hidden_dynamic_lds_size
    .group_segment_fixed_size: 0
    .kernarg_segment_align: 8
    .kernarg_segment_size: 424
    .language:       OpenCL C
    .language_version:
      - 2
      - 0
    .max_flat_workgroup_size: 512
    .name:           _Z6mk_fwd4Args
    .private_segment_fixed_size: 0
    .sgpr_count:     108
    .sgpr_spill_count: 31
    .symbol:         _Z6mk_fwd4Args.kd
    .uniform_work_group_size: 1
    .uses_dynamic_stack: false
    .vgpr_count:     256
    .vgpr_spill_count: 0
    .wavefront_size: 64
